# cvhost: one output column (8 rows) per slot with a full 16-B store per lane (full-line writes) instead of partial dword stores; 8 dword loads + wait vmcnt(8)
# baseline (speedup 1.0000x reference)
; #define GAS __attribute__((address_space(1)))
; __device__ __forceinline__ P0Desc p0_desc(int r, int lane, const P0Ptrs& a) {
;     const int kk = lane >> 3, n4 = (lane & 7) * 4; P0Desc d; d.gs = 1.f;
;     int kb, n, sc, nsrc, ldt; const float* W; bf16_t* WT; const float* ks;
;     if (r < F_O) { kb = r >> 6; n = 32 * (r & 63) + n4; sc = n; W = a.w_o; nsrc = 2048; WT = a.WoT; ldt = 2048; ks = (kb < 16) ? a.on_a : (a.on_c - 1024); }
;     else if ((r -= F_O) < F_UP) { kb = r / 352; n = 32 * (r % 352) + n4; sc = ((n >> 7) & 1) * DFF + (n >> 8) * 128 + (n & 127); W = a.w_up; nsrc = 2 * DFF; WT = a.WupT; ldt = 2048; ks = a.ffn_g; }
;     else if ((r -= F_UP) < F_DN) { kb = r >> 6; n = 32 * (r & 63) + n4; sc = n; W = a.w_dn; nsrc = 2048; WT = a.WdT; ldt = DFF; ks = nullptr; }
;     else if ((r -= F_DN) < F_IN) { kb = r >> 7; n = 32 * (r & 127) + n4;
;         if (n < 1024) sc = n; else if (n < 2048) sc = n + 64; else sc = (((n >> 7) & 1) ? 3136 : 2112) + 128 * ((n - 2048) >> 8) + (n & 127);
;         W = a.w_in; nsrc = INW; WT = a.WinT; ldt = 2048; ks = a.attn_g; }
;     else if ((r -= F_IN) < F_Q) { kb = r >> 5; n = 32 * (6 * ((r & 31) >> 2) + (r & 3)) + n4; sc = n; W = a.w_qb; nsrc = 1536; WT = a.WqT; ldt = 2048; ks = a.qa_g; d.gs = QSCALE; }
;     else { r -= F_Q; kb = r >> 6; n = 32 * (r & 63) + n4; sc = n; W = a.w_kvb; nsrc = 2048; WT = a.WkvT; ldt = 2048; ks = a.kva_g; }
;     const int k0 = 64 * kb + 8 * kk;
;     d.src = W + (size_t)k0 * nsrc + sc; d.nsrc = nsrc; d.dst = WT + (size_t)n * ldt + k0; d.ldt = ldt; d.ks = ks ? ks + k0 : nullptr;
;     return d;
; }
; template <int NB>
; __device__ __forceinline__ void p0_batch(int it0, int stride, int lane, const P0Ptrs& a) {
;     ...
;     for (int q = 0; q < NB; ++q) {
;         const float gs = d[q].gs; const bool hk = d[q].ks != nullptr;
;         const f32x4 t0 = hk ? s0[q] * gs : (f32x4){gs, gs, gs, gs}, t1 = hk ? s1[q] * gs : (f32x4){gs, gs, gs, gs};
; #pragma unroll
;         for (int i = 0; i < 4; ++i) { v[q][i] *= t0[i]; v[q][4 + i] *= t1[i]; }
;         if (d[q].dst) {
; #pragma unroll
;             for (int e = 0; e < 4; ++e) { u32x4 o; o.x = cvt_pk_bf16(v[q][0][e], v[q][1][e]); o.y = cvt_pk_bf16(v[q][2][e], v[q][3][e]); o.z = cvt_pk_bf16(v[q][4][e], v[q][5][e]); o.w = cvt_pk_bf16(v[q][6][e], v[q][7][e]);
;                 *(GAS u32x4*)(d[q].dst + (size_t)e * d[q].ldt) = o; } }
;     }
.LBB0_759:
	v_lshl_add_u64 v[112:113], s[28:29], 0, v[146:147]
	s_mov_b64 s[54:55], 0x18fc0000
	s_mov_b32 m0, s78
	v_lshl_add_u64 v[100:101], v[112:113], 0, s[54:55]
	s_waitcnt vmcnt(0)
	s_barrier
	global_load_lds_dwordx4 v[100:101], off
	v_lshl_add_u64 v[100:101], v[112:113], 0, s[38:39]
	s_add_i32 m0, s78, 0x2000
	v_lshl_add_u64 v[136:137], s[28:29], 0, v[144:145]
	global_load_lds_dwordx4 v[100:101], off
	v_lshl_add_u64 v[100:101], v[136:137], 0, s[40:41]
	s_add_i32 m0, s78, 0x4000
	v_lshl_add_u64 v[134:135], s[28:29], 0, v[148:149]
	global_load_lds_dwordx4 v[100:101], off
	v_lshl_add_u64 v[100:101], v[134:135], 0, s[42:43]
	s_mov_b32 m0, s58
	global_load_lds_dwordx4 v[100:101], off
	v_lshl_add_u64 v[100:101], v[134:135], 0, s[44:45]
	s_mov_b32 m0, s77
	global_load_lds_dwordx4 v[100:101], off
	s_cmp_gt_u32 s87, 20
	s_cbranch_scc1 .Lcv_done
	s_cmp_eq_u32 s87, 0
	s_cbranch_scc1 .Lcv_nocons
	s_cmp_gt_u32 s32, 6
	s_cbranch_scc1 .Lcv_nomul
	v_mul_f32_e32 v237, v238, v237
	v_mul_f32_e32 v246, v239, v246
	v_mul_f32_e32 v250, v240, v250
	v_mul_f32_e32 v251, v241, v251
	v_mul_f32_e32 v252, v242, v252
	v_mul_f32_e32 v253, v243, v253
	v_mul_f32_e32 v254, v244, v254
	v_mul_f32_e32 v255, v245, v255
.Lcv_nomul:
	v_and_b32_e32 v83, 7, v0
	v_bfe_u32 v82, v0, 3, 3
	s_lshl_b32 s98, s91, 2
	v_cvt_pk_bf16_f32 v76, v237, v246
	v_cvt_pk_bf16_f32 v77, v250, v251
	v_mul_u32_u24_e32 v81, s98, v83
	v_cvt_pk_bf16_f32 v78, v252, v253
	v_cvt_pk_bf16_f32 v79, v254, v255
	v_lshl_add_u32 v81, v82, 4, v81
	s_nop 0
	global_store_dwordx4 v81, v[76:79], s[92:93]
	s_add_u32 s92, s92, s91
	s_addc_u32 s93, s93, 0
.Lcv_nocons:
	s_cmp_gt_u32 s87, 19
	s_cbranch_scc1 .Lcv_inc
	s_and_b32 s98, s87, 3
	s_cmp_lg_u32 s98, 0
	s_cbranch_scc1 .Lcv_loads
	s_add_i32 s32, s32, 1
	v_readfirstlane_b32 s99, v0
	s_waitcnt lgkmcnt(0)
	s_and_b32 s98, s2, 0xff
	s_lshr_b32 s90, s98, 3
	s_and_b32 s98, s98, 7
	s_lshl_b32 s98, s98, 3
	s_lshr_b32 s99, s99, 6
	s_add_i32 s91, s98, s99
	s_cmp_eq_u32 s32, 0
	s_cbranch_scc1 .Lcv_t0
	s_cmp_lt_u32 s32, 7
	s_cbranch_scc1 .Lcv_t1
	s_add_i32 s98, s32, -7
	s_lshl_b32 s98, s98, 5
	s_add_i32 s90, s90, s98
	s_cmp_ge_u32 s90, 0x58
	s_cselect_b32 s98, 32, 0
	s_sub_i32 s90, s90, s98
	s_lshl_b32 s98, s90, 19
	s_lshl_b32 s99, s91, 7
	s_add_i32 s98, s98, s99
	s_add_u32 s88, s88, s98
	s_addc_u32 s89, s89, 0
	s_mul_i32 s98, s91, 0x58000
	s_lshl_b32 s99, s90, 7
	s_add_i32 s98, s98, s99
	s_add_i32 s98, s98, 0x6900000
	s_add_u32 s92, s28, s98
	s_addc_u32 s93, s29, 0
	s_mov_b32 s90, 0x2000
	s_mov_b32 s91, 0x2c00
	s_branch .Lcv_s2done
.Lcv_t1:
	s_add_i32 s98, s32, -1
	s_lshl_b32 s98, s98, 6
	s_add_i32 s91, s91, s98
	s_cmp_ge_u32 s91, 0x160
	s_cselect_b32 s98, 64, 0
	s_sub_i32 s91, s91, s98
	s_bfe_u32 s98, s91, 0x10002
	s_mul_i32 s98, s98, 0x5800
	s_lshr_b32 s99, s91, 3
	s_lshl_b32 s99, s99, 9
	s_add_i32 s98, s98, s99
	s_and_b32 s99, s91, 3
	s_lshl_b32 s99, s99, 7
	s_add_i32 s98, s98, s99
	s_mul_i32 s99, s90, 0x2c0000
	s_add_i32 s98, s98, s99
	s_add_u32 s88, s88, s98
	s_addc_u32 s89, s89, 0
	s_lshl_b32 s98, s90, 8
	s_add_u32 s94, s94, s98
	s_addc_u32 s95, s95, 0
	s_lshl_b32 s98, s91, 17
	s_lshl_b32 s99, s90, 7
	s_add_i32 s98, s98, s99
	s_add_i32 s98, s98, 0x3d00000
	s_add_u32 s92, s28, s98
	s_addc_u32 s93, s29, 0
	s_mov_b32 s90, 0xb000
	s_mov_b32 s91, 0x1000
	s_branch .Lcv_s2done

; template <int NB>
; __device__ __forceinline__ void p0_batch(int it0, int stride, int lane, const P0Ptrs& a) {
;     f32x4 v[NB][8], s0[NB], s1[NB]; P0Desc d[NB];
; #pragma unroll
;     for (int q = 0; q < NB; ++q) { const bool ok = it0 < NFAST / 4; d[q] = p0_desc(p0_super(ok ? it0 : 0, q), lane, a); if (!ok) d[q].dst = nullptr;
; #pragma unroll
;         for (int i = 0; i < 8; ++i) v[q][i] = __builtin_nontemporal_load((const f32x4*)(d[q].src + (size_t)i * d[q].nsrc));
;         const float* kp = d[q].ks ? d[q].ks : a.ffn_g;
;         s0[q] = *(const f32x4*)(kp); s1[q] = *(const f32x4*)(kp + 4); }
.Lcv_s2done:
	v_bfe_u32 v82, v0, 3, 3
	v_lshlrev_b32_e32 v82, 5, v82
	s_nop 0
	global_load_dwordx4 v[238:241], v82, s[94:95]
	global_load_dwordx4 v[242:245], v82, s[94:95] offset:16
.Lcv_loads:
	v_and_b32_e32 v83, 7, v0
	v_bfe_u32 v82, v0, 3, 3
	s_lshl_b32 s98, s90, 3
	v_lshlrev_b32_e32 v83, 4, v83
	v_mad_u32_u24 v80, v82, s98, v83
	s_mov_b64 s[98:99], s[88:89]
	global_load_dword v237, v80, s[98:99]
	s_add_u32 s98, s98, s90
	s_addc_u32 s99, s99, 0
	global_load_dword v246, v80, s[98:99]
	s_add_u32 s98, s98, s90
	s_addc_u32 s99, s99, 0
	global_load_dword v250, v80, s[98:99]
	s_add_u32 s98, s98, s90
	s_addc_u32 s99, s99, 0
	global_load_dword v251, v80, s[98:99]
	s_add_u32 s98, s98, s90
	s_addc_u32 s99, s99, 0
	global_load_dword v252, v80, s[98:99]
	s_add_u32 s98, s98, s90
	s_addc_u32 s99, s99, 0
	global_load_dword v253, v80, s[98:99]
	s_add_u32 s98, s98, s90
	s_addc_u32 s99, s99, 0
	global_load_dword v254, v80, s[98:99]
	s_add_u32 s98, s98, s90
	s_addc_u32 s99, s99, 0
	global_load_dword v255, v80, s[98:99]
	s_add_u32 s88, s88, 4
	s_addc_u32 s89, s89, 0
	s_and_b32 s98, s87, 3
	s_cmp_lg_u32 s98, 3
	s_cbranch_scc1 .Lcv_inc
	s_cmp_gt_u32 s87, 18
	s_cbranch_scc1 .Lcv_inc
	s_add_i32 s99, s32, 1
	s_movk_i32 s98, 0x78
	s_cmp_lt_u32 s99, 7
	s_cselect_b32 s98, 0x60, s98
	s_cmp_eq_u32 s99, 0
	s_cselect_b32 s98, 0x50, s98
	s_cselect_b32 s99, 0, 0x58
	s_load_dwordx2 s[88:89], s[100:101], s98
	s_cmp_eq_u32 s99, 0
	s_cbranch_scc0 .Lcv_s1b_s
	s_bfe_u32 s99, s2, 0x50003
	s_cmp_lt_u32 s99, 16
	s_cselect_b32 s99, 64, 0x48

.Lcv_w3:
	s_waitcnt vmcnt(8)
